# kmean loop software-pipelined + NSA selected loop list/K reads hoisted above scalar bookkeeping
# speedup vs baseline: 1.0094x; 1.0094x over previous
; DI int opaque(int v) { asm volatile("" : "+v"(v)); return v; }
; DI void kmean_item(const float* __restrict__ base, const int* __restrict__ pt, int b, int n, float* __restrict__ outp, char* sm) {
;     float* scr = (float*)sm;
;     const int t = opaque(threadIdx.x), lane = t & 63, w = t >> 6;
;     f32x4 a0 = {0.f, 0.f, 0.f, 0.f}, a1 = {0.f, 0.f, 0.f, 0.f};
; #pragma unroll
;     for (int hf = 0; hf < 2; ++hf) {
;         const int pos0 = n * 256 + hf * 128;
;         const size_t r0 = pt ? (size_t)pt[b * 64 + (pos0 >> 7)] * 128 : (size_t)b * 8192 + pos0;
;         const float* rp = base + (r0 + w) * 1024 + lane * 4;
; #pragma unroll 4
;         for (int rr = 0; rr < 32; ++rr) {
;             a0 += __builtin_nontemporal_load((const f32x4*)(rp + (size_t)rr * 4096));
;             a1 += __builtin_nontemporal_load((const f32x4*)(rp + (size_t)rr * 4096 + 256));
;         }
;     }
;     *(f32x4*)(scr + w * 512 + lane * 4) = a0;
;     *(f32x4*)(scr + w * 512 + 256 + lane * 4) = a1;
;     __syncthreads();
; #pragma unroll
;     for (int j = 0; j < 2; ++j) {
;         const int col = t + 256 * j;
;         outp[col] = (scr[col] + scr[512 + col] + scr[1024 + col] + scr[1536 + col]) * (1.f / 256.f);
;     }
;     __syncthreads();
; }
.LBB0_93:
	s_andn2_b64 vcc, exec, s[2:3]
	s_cbranch_vccnz .LBB0_105
	s_add_i32 s2, s97, 0xffffff40
	s_lshr_b32 s52, s2, 5
	s_and_b32 s53, s97, 31
	v_mov_b32_e32 v10, v0
	s_lshl_b32 s3, s52, 6
	s_andn2_b64 vcc, exec, s[70:71]
	s_cbranch_vccnz .Lkm_nopt
	s_lshl_b32 s6, s53, 1
	s_or_b32 s74, s3, s6
	s_lshl_b64 s[6:7], s[74:75], 2
	s_add_u32 s6, s50, s6
	s_addc_u32 s7, s51, s7
	global_load_dwordx2 v[2:3], v19, s[6:7]
	s_lshl_b32 s53, s53, 8
	s_lshl_b32 s52, s52, 13
	s_waitcnt vmcnt(0)
	v_lshlrev_b32_e32 v2, 7, v2
	v_lshlrev_b32_e32 v3, 7, v3
	s_branch .Lkm_go
.Lkm_nopt:
	s_lshl_b32 s53, s53, 8
	s_lshl_b32 s52, s52, 13
	s_or_b32 s6, s52, s53
	v_mov_b32_e32 v2, s6
	s_bitset1_b32 s6, 7
	v_mov_b32_e32 v3, s6
.Lkm_go:
	s_bitset1_b32 s53, 7
	v_ashrrev_i32_e32 v12, 6, v10
	v_lshlrev_b32_e32 v1, 2, v10
	v_and_b32_e32 v1, 0xfc, v1
	v_lshlrev_b32_e32 v18, 2, v1
	v_add_lshl_u32 v2, v2, v12, 12
	v_add_lshl_u32 v3, v3, v12, 12
	v_add_u32_e32 v172, v2, v18
	v_add_u32_e32 v176, v3, v18
	v_add_u32_e32 v173, 0x4000, v172
	v_add_u32_e32 v177, 0x4000, v176
	v_add_u32_e32 v174, 0x8000, v172
	v_add_u32_e32 v178, 0x8000, v176
	v_add_u32_e32 v175, 0xc000, v172
	v_add_u32_e32 v179, 0xc000, v176
	v_mov_b32_e32 v2, 0
	v_mov_b32_e32 v3, v2
	v_mov_b32_e32 v4, v2
	v_mov_b32_e32 v5, v2
	v_mov_b32_e32 v6, v2
	v_mov_b32_e32 v7, v2
	v_mov_b32_e32 v8, v2
	v_mov_b32_e32 v9, v2
	s_mov_b64 s[6:7], s[44:45]
	global_load_dwordx4 v[26:29], v172, s[6:7] nt
	global_load_dwordx4 v[30:33], v172, s[6:7] offset:1024 nt
	global_load_dwordx4 v[34:37], v173, s[6:7] nt
	global_load_dwordx4 v[38:41], v173, s[6:7] offset:1024 nt
	global_load_dwordx4 v[42:45], v174, s[6:7] nt
	global_load_dwordx4 v[46:49], v174, s[6:7] offset:1024 nt
	global_load_dwordx4 v[50:53], v175, s[6:7] nt
	global_load_dwordx4 v[54:57], v175, s[6:7] offset:1024 nt
	s_add_u32 s6, s44, 0x10000
	s_addc_u32 s7, s45, 0
	global_load_dwordx4 v[140:143], v172, s[6:7] nt
	global_load_dwordx4 v[144:147], v172, s[6:7] offset:1024 nt
	global_load_dwordx4 v[148:151], v173, s[6:7] nt
	global_load_dwordx4 v[152:155], v173, s[6:7] offset:1024 nt
	global_load_dwordx4 v[156:159], v174, s[6:7] nt
	global_load_dwordx4 v[160:163], v174, s[6:7] offset:1024 nt
	global_load_dwordx4 v[164:167], v175, s[6:7] nt
	global_load_dwordx4 v[168:171], v175, s[6:7] offset:1024 nt
	s_waitcnt vmcnt(15)
	v_pk_add_f32 v[2:3], v[2:3], v[26:27]
	v_pk_add_f32 v[4:5], v[4:5], v[28:29]
	s_waitcnt vmcnt(14)
	v_pk_add_f32 v[6:7], v[6:7], v[30:31]
	v_pk_add_f32 v[8:9], v[8:9], v[32:33]
	s_waitcnt vmcnt(13)
	v_pk_add_f32 v[2:3], v[2:3], v[34:35]
	v_pk_add_f32 v[4:5], v[4:5], v[36:37]
	s_waitcnt vmcnt(12)
	v_pk_add_f32 v[6:7], v[6:7], v[38:39]
	v_pk_add_f32 v[8:9], v[8:9], v[40:41]
	s_waitcnt vmcnt(11)
	v_pk_add_f32 v[2:3], v[2:3], v[42:43]
	v_pk_add_f32 v[4:5], v[4:5], v[44:45]
	s_waitcnt vmcnt(10)
	v_pk_add_f32 v[6:7], v[6:7], v[46:47]
	v_pk_add_f32 v[8:9], v[8:9], v[48:49]
	s_waitcnt vmcnt(9)
	v_pk_add_f32 v[2:3], v[2:3], v[50:51]
	v_pk_add_f32 v[4:5], v[4:5], v[52:53]
	s_waitcnt vmcnt(8)
	v_pk_add_f32 v[6:7], v[6:7], v[54:55]
	v_pk_add_f32 v[8:9], v[8:9], v[56:57]
	s_add_u32 s6, s44, 0x20000
	s_addc_u32 s7, s45, 0
	global_load_dwordx4 v[26:29], v172, s[6:7] nt
	global_load_dwordx4 v[30:33], v172, s[6:7] offset:1024 nt
	global_load_dwordx4 v[34:37], v173, s[6:7] nt
	global_load_dwordx4 v[38:41], v173, s[6:7] offset:1024 nt
	global_load_dwordx4 v[42:45], v174, s[6:7] nt
	global_load_dwordx4 v[46:49], v174, s[6:7] offset:1024 nt
	global_load_dwordx4 v[50:53], v175, s[6:7] nt
	global_load_dwordx4 v[54:57], v175, s[6:7] offset:1024 nt
	s_waitcnt vmcnt(15)
	v_pk_add_f32 v[2:3], v[2:3], v[140:141]
	v_pk_add_f32 v[4:5], v[4:5], v[142:143]
	s_waitcnt vmcnt(14)
	v_pk_add_f32 v[6:7], v[6:7], v[144:145]
	v_pk_add_f32 v[8:9], v[8:9], v[146:147]
	s_waitcnt vmcnt(13)
	v_pk_add_f32 v[2:3], v[2:3], v[148:149]
	v_pk_add_f32 v[4:5], v[4:5], v[150:151]
	s_waitcnt vmcnt(12)
	v_pk_add_f32 v[6:7], v[6:7], v[152:153]
	v_pk_add_f32 v[8:9], v[8:9], v[154:155]
	s_waitcnt vmcnt(11)
	v_pk_add_f32 v[2:3], v[2:3], v[156:157]
	v_pk_add_f32 v[4:5], v[4:5], v[158:159]
	s_waitcnt vmcnt(10)
	v_pk_add_f32 v[6:7], v[6:7], v[160:161]
	v_pk_add_f32 v[8:9], v[8:9], v[162:163]
	s_waitcnt vmcnt(9)
	v_pk_add_f32 v[2:3], v[2:3], v[164:165]
	v_pk_add_f32 v[4:5], v[4:5], v[166:167]
	s_waitcnt vmcnt(8)
	v_pk_add_f32 v[6:7], v[6:7], v[168:169]
	v_pk_add_f32 v[8:9], v[8:9], v[170:171]
	s_add_u32 s6, s44, 0x30000
	s_addc_u32 s7, s45, 0
	global_load_dwordx4 v[140:143], v172, s[6:7] nt
	global_load_dwordx4 v[144:147], v172, s[6:7] offset:1024 nt
	global_load_dwordx4 v[148:151], v173, s[6:7] nt
	global_load_dwordx4 v[152:155], v173, s[6:7] offset:1024 nt
	global_load_dwordx4 v[156:159], v174, s[6:7] nt
	global_load_dwordx4 v[160:163], v174, s[6:7] offset:1024 nt
	global_load_dwordx4 v[164:167], v175, s[6:7] nt
	global_load_dwordx4 v[168:171], v175, s[6:7] offset:1024 nt
	s_waitcnt vmcnt(15)
	v_pk_add_f32 v[2:3], v[2:3], v[26:27]
	v_pk_add_f32 v[4:5], v[4:5], v[28:29]
	s_waitcnt vmcnt(14)
	v_pk_add_f32 v[6:7], v[6:7], v[30:31]
	v_pk_add_f32 v[8:9], v[8:9], v[32:33]
	s_waitcnt vmcnt(13)
	v_pk_add_f32 v[2:3], v[2:3], v[34:35]
	v_pk_add_f32 v[4:5], v[4:5], v[36:37]
	s_waitcnt vmcnt(12)
	v_pk_add_f32 v[6:7], v[6:7], v[38:39]
	v_pk_add_f32 v[8:9], v[8:9], v[40:41]
	s_waitcnt vmcnt(11)
	v_pk_add_f32 v[2:3], v[2:3], v[42:43]
	v_pk_add_f32 v[4:5], v[4:5], v[44:45]
	s_waitcnt vmcnt(10)
	v_pk_add_f32 v[6:7], v[6:7], v[46:47]
	v_pk_add_f32 v[8:9], v[8:9], v[48:49]
	s_waitcnt vmcnt(9)
	v_pk_add_f32 v[2:3], v[2:3], v[50:51]
	v_pk_add_f32 v[4:5], v[4:5], v[52:53]
	s_waitcnt vmcnt(8)
; DI void kmean_item(const float* __restrict__ base, const int* __restrict__ pt, int b, int n, float* __restrict__ outp, char* sm) {
;     ...
;     for (int hf = 0; hf < 2; ++hf) {
;         const int pos0 = n * 256 + hf * 128;
;         const size_t r0 = pt ? (size_t)pt[b * 64 + (pos0 >> 7)] * 128 : (size_t)b * 8192 + pos0;
;         const float* rp = base + (r0 + w) * 1024 + lane * 4;
; #pragma unroll 4
;         for (int rr = 0; rr < 32; ++rr) {
;             a0 += __builtin_nontemporal_load((const f32x4*)(rp + (size_t)rr * 4096));
;             a1 += __builtin_nontemporal_load((const f32x4*)(rp + (size_t)rr * 4096 + 256));
;         }
	v_pk_add_f32 v[6:7], v[6:7], v[54:55]
	v_pk_add_f32 v[8:9], v[8:9], v[56:57]
	s_add_u32 s6, s44, 0x40000
	s_addc_u32 s7, s45, 0
	global_load_dwordx4 v[26:29], v172, s[6:7] nt
	global_load_dwordx4 v[30:33], v172, s[6:7] offset:1024 nt
	global_load_dwordx4 v[34:37], v173, s[6:7] nt
	global_load_dwordx4 v[38:41], v173, s[6:7] offset:1024 nt
	global_load_dwordx4 v[42:45], v174, s[6:7] nt
	global_load_dwordx4 v[46:49], v174, s[6:7] offset:1024 nt
	global_load_dwordx4 v[50:53], v175, s[6:7] nt
	global_load_dwordx4 v[54:57], v175, s[6:7] offset:1024 nt
	s_waitcnt vmcnt(15)
	v_pk_add_f32 v[2:3], v[2:3], v[140:141]
	v_pk_add_f32 v[4:5], v[4:5], v[142:143]
	s_waitcnt vmcnt(14)
	v_pk_add_f32 v[6:7], v[6:7], v[144:145]
	v_pk_add_f32 v[8:9], v[8:9], v[146:147]
	s_waitcnt vmcnt(13)
	v_pk_add_f32 v[2:3], v[2:3], v[148:149]
	v_pk_add_f32 v[4:5], v[4:5], v[150:151]
	s_waitcnt vmcnt(12)
	v_pk_add_f32 v[6:7], v[6:7], v[152:153]
	v_pk_add_f32 v[8:9], v[8:9], v[154:155]
	s_waitcnt vmcnt(11)
	v_pk_add_f32 v[2:3], v[2:3], v[156:157]
	v_pk_add_f32 v[4:5], v[4:5], v[158:159]
	s_waitcnt vmcnt(10)
	v_pk_add_f32 v[6:7], v[6:7], v[160:161]
	v_pk_add_f32 v[8:9], v[8:9], v[162:163]
	s_waitcnt vmcnt(9)
	v_pk_add_f32 v[2:3], v[2:3], v[164:165]
	v_pk_add_f32 v[4:5], v[4:5], v[166:167]
	s_waitcnt vmcnt(8)
	v_pk_add_f32 v[6:7], v[6:7], v[168:169]
	v_pk_add_f32 v[8:9], v[8:9], v[170:171]
	s_add_u32 s6, s44, 0x50000
	s_addc_u32 s7, s45, 0
	global_load_dwordx4 v[140:143], v172, s[6:7] nt
	global_load_dwordx4 v[144:147], v172, s[6:7] offset:1024 nt
	global_load_dwordx4 v[148:151], v173, s[6:7] nt
	global_load_dwordx4 v[152:155], v173, s[6:7] offset:1024 nt
	global_load_dwordx4 v[156:159], v174, s[6:7] nt
	global_load_dwordx4 v[160:163], v174, s[6:7] offset:1024 nt
	global_load_dwordx4 v[164:167], v175, s[6:7] nt
	global_load_dwordx4 v[168:171], v175, s[6:7] offset:1024 nt
	s_waitcnt vmcnt(15)
	v_pk_add_f32 v[2:3], v[2:3], v[26:27]
	v_pk_add_f32 v[4:5], v[4:5], v[28:29]
	s_waitcnt vmcnt(14)
	v_pk_add_f32 v[6:7], v[6:7], v[30:31]
	v_pk_add_f32 v[8:9], v[8:9], v[32:33]
	s_waitcnt vmcnt(13)
	v_pk_add_f32 v[2:3], v[2:3], v[34:35]
	v_pk_add_f32 v[4:5], v[4:5], v[36:37]
	s_waitcnt vmcnt(12)
	v_pk_add_f32 v[6:7], v[6:7], v[38:39]
	v_pk_add_f32 v[8:9], v[8:9], v[40:41]
	s_waitcnt vmcnt(11)
	v_pk_add_f32 v[2:3], v[2:3], v[42:43]
	v_pk_add_f32 v[4:5], v[4:5], v[44:45]
	s_waitcnt vmcnt(10)
	v_pk_add_f32 v[6:7], v[6:7], v[46:47]
	v_pk_add_f32 v[8:9], v[8:9], v[48:49]
	s_waitcnt vmcnt(9)
	v_pk_add_f32 v[2:3], v[2:3], v[50:51]
	v_pk_add_f32 v[4:5], v[4:5], v[52:53]
	s_waitcnt vmcnt(8)
	v_pk_add_f32 v[6:7], v[6:7], v[54:55]
	v_pk_add_f32 v[8:9], v[8:9], v[56:57]
	s_add_u32 s6, s44, 0x60000
	s_addc_u32 s7, s45, 0
	global_load_dwordx4 v[26:29], v172, s[6:7] nt
	global_load_dwordx4 v[30:33], v172, s[6:7] offset:1024 nt
	global_load_dwordx4 v[34:37], v173, s[6:7] nt
	global_load_dwordx4 v[38:41], v173, s[6:7] offset:1024 nt
	global_load_dwordx4 v[42:45], v174, s[6:7] nt
	global_load_dwordx4 v[46:49], v174, s[6:7] offset:1024 nt
	global_load_dwordx4 v[50:53], v175, s[6:7] nt
	global_load_dwordx4 v[54:57], v175, s[6:7] offset:1024 nt
	s_waitcnt vmcnt(15)
	v_pk_add_f32 v[2:3], v[2:3], v[140:141]
	v_pk_add_f32 v[4:5], v[4:5], v[142:143]
	s_waitcnt vmcnt(14)
	v_pk_add_f32 v[6:7], v[6:7], v[144:145]
	v_pk_add_f32 v[8:9], v[8:9], v[146:147]
	s_waitcnt vmcnt(13)
	v_pk_add_f32 v[2:3], v[2:3], v[148:149]
	v_pk_add_f32 v[4:5], v[4:5], v[150:151]
	s_waitcnt vmcnt(12)
	v_pk_add_f32 v[6:7], v[6:7], v[152:153]
	v_pk_add_f32 v[8:9], v[8:9], v[154:155]
	s_waitcnt vmcnt(11)
	v_pk_add_f32 v[2:3], v[2:3], v[156:157]
	v_pk_add_f32 v[4:5], v[4:5], v[158:159]
	s_waitcnt vmcnt(10)
	v_pk_add_f32 v[6:7], v[6:7], v[160:161]
	v_pk_add_f32 v[8:9], v[8:9], v[162:163]
	s_waitcnt vmcnt(9)
	v_pk_add_f32 v[2:3], v[2:3], v[164:165]
	v_pk_add_f32 v[4:5], v[4:5], v[166:167]
	s_waitcnt vmcnt(8)
	v_pk_add_f32 v[6:7], v[6:7], v[168:169]
	v_pk_add_f32 v[8:9], v[8:9], v[170:171]
	s_add_u32 s6, s44, 0x70000
	s_addc_u32 s7, s45, 0
	global_load_dwordx4 v[140:143], v172, s[6:7] nt
	global_load_dwordx4 v[144:147], v172, s[6:7] offset:1024 nt
	global_load_dwordx4 v[148:151], v173, s[6:7] nt
	global_load_dwordx4 v[152:155], v173, s[6:7] offset:1024 nt
	global_load_dwordx4 v[156:159], v174, s[6:7] nt
	global_load_dwordx4 v[160:163], v174, s[6:7] offset:1024 nt
	global_load_dwordx4 v[164:167], v175, s[6:7] nt
	global_load_dwordx4 v[168:171], v175, s[6:7] offset:1024 nt
	s_waitcnt vmcnt(15)
	v_pk_add_f32 v[2:3], v[2:3], v[26:27]
	v_pk_add_f32 v[4:5], v[4:5], v[28:29]
	s_waitcnt vmcnt(14)
	v_pk_add_f32 v[6:7], v[6:7], v[30:31]
	v_pk_add_f32 v[8:9], v[8:9], v[32:33]
	s_waitcnt vmcnt(13)
	v_pk_add_f32 v[2:3], v[2:3], v[34:35]
	v_pk_add_f32 v[4:5], v[4:5], v[36:37]
	s_waitcnt vmcnt(12)
	v_pk_add_f32 v[6:7], v[6:7], v[38:39]
	v_pk_add_f32 v[8:9], v[8:9], v[40:41]
	s_waitcnt vmcnt(11)
	v_pk_add_f32 v[2:3], v[2:3], v[42:43]
	v_pk_add_f32 v[4:5], v[4:5], v[44:45]
	s_waitcnt vmcnt(10)
	v_pk_add_f32 v[6:7], v[6:7], v[46:47]
	v_pk_add_f32 v[8:9], v[8:9], v[48:49]
	s_waitcnt vmcnt(9)
	v_pk_add_f32 v[2:3], v[2:3], v[50:51]
	v_pk_add_f32 v[4:5], v[4:5], v[52:53]
	s_waitcnt vmcnt(8)
	v_pk_add_f32 v[6:7], v[6:7], v[54:55]
	v_pk_add_f32 v[8:9], v[8:9], v[56:57]
	s_mov_b64 s[6:7], s[44:45]
	global_load_dwordx4 v[26:29], v176, s[6:7] nt
	global_load_dwordx4 v[30:33], v176, s[6:7] offset:1024 nt
	global_load_dwordx4 v[34:37], v177, s[6:7] nt
	global_load_dwordx4 v[38:41], v177, s[6:7] offset:1024 nt
	global_load_dwordx4 v[42:45], v178, s[6:7] nt
	global_load_dwordx4 v[46:49], v178, s[6:7] offset:1024 nt
	global_load_dwordx4 v[50:53], v179, s[6:7] nt
	global_load_dwordx4 v[54:57], v179, s[6:7] offset:1024 nt
	s_waitcnt vmcnt(15)
; DI void kmean_item(const float* __restrict__ base, const int* __restrict__ pt, int b, int n, float* __restrict__ outp, char* sm) {
;     ...
;     for (int hf = 0; hf < 2; ++hf) {
;         const int pos0 = n * 256 + hf * 128;
;         const size_t r0 = pt ? (size_t)pt[b * 64 + (pos0 >> 7)] * 128 : (size_t)b * 8192 + pos0;
;         const float* rp = base + (r0 + w) * 1024 + lane * 4;
; #pragma unroll 4
;         for (int rr = 0; rr < 32; ++rr) {
;             a0 += __builtin_nontemporal_load((const f32x4*)(rp + (size_t)rr * 4096));
;             a1 += __builtin_nontemporal_load((const f32x4*)(rp + (size_t)rr * 4096 + 256));
;         }
	v_pk_add_f32 v[2:3], v[2:3], v[140:141]
	v_pk_add_f32 v[4:5], v[4:5], v[142:143]
	s_waitcnt vmcnt(14)
	v_pk_add_f32 v[6:7], v[6:7], v[144:145]
	v_pk_add_f32 v[8:9], v[8:9], v[146:147]
	s_waitcnt vmcnt(13)
	v_pk_add_f32 v[2:3], v[2:3], v[148:149]
	v_pk_add_f32 v[4:5], v[4:5], v[150:151]
	s_waitcnt vmcnt(12)
	v_pk_add_f32 v[6:7], v[6:7], v[152:153]
	v_pk_add_f32 v[8:9], v[8:9], v[154:155]
	s_waitcnt vmcnt(11)
	v_pk_add_f32 v[2:3], v[2:3], v[156:157]
	v_pk_add_f32 v[4:5], v[4:5], v[158:159]
	s_waitcnt vmcnt(10)
	v_pk_add_f32 v[6:7], v[6:7], v[160:161]
	v_pk_add_f32 v[8:9], v[8:9], v[162:163]
	s_waitcnt vmcnt(9)
	v_pk_add_f32 v[2:3], v[2:3], v[164:165]
	v_pk_add_f32 v[4:5], v[4:5], v[166:167]
	s_waitcnt vmcnt(8)
	v_pk_add_f32 v[6:7], v[6:7], v[168:169]
	v_pk_add_f32 v[8:9], v[8:9], v[170:171]
	s_add_u32 s6, s44, 0x10000
	s_addc_u32 s7, s45, 0
	global_load_dwordx4 v[140:143], v176, s[6:7] nt
	global_load_dwordx4 v[144:147], v176, s[6:7] offset:1024 nt
	global_load_dwordx4 v[148:151], v177, s[6:7] nt
	global_load_dwordx4 v[152:155], v177, s[6:7] offset:1024 nt
	global_load_dwordx4 v[156:159], v178, s[6:7] nt
	global_load_dwordx4 v[160:163], v178, s[6:7] offset:1024 nt
	global_load_dwordx4 v[164:167], v179, s[6:7] nt
	global_load_dwordx4 v[168:171], v179, s[6:7] offset:1024 nt
	s_waitcnt vmcnt(15)
	v_pk_add_f32 v[2:3], v[2:3], v[26:27]
	v_pk_add_f32 v[4:5], v[4:5], v[28:29]
	s_waitcnt vmcnt(14)
	v_pk_add_f32 v[6:7], v[6:7], v[30:31]
	v_pk_add_f32 v[8:9], v[8:9], v[32:33]
	s_waitcnt vmcnt(13)
	v_pk_add_f32 v[2:3], v[2:3], v[34:35]
	v_pk_add_f32 v[4:5], v[4:5], v[36:37]
	s_waitcnt vmcnt(12)
	v_pk_add_f32 v[6:7], v[6:7], v[38:39]
	v_pk_add_f32 v[8:9], v[8:9], v[40:41]
	s_waitcnt vmcnt(11)
	v_pk_add_f32 v[2:3], v[2:3], v[42:43]
	v_pk_add_f32 v[4:5], v[4:5], v[44:45]
	s_waitcnt vmcnt(10)
	v_pk_add_f32 v[6:7], v[6:7], v[46:47]
	v_pk_add_f32 v[8:9], v[8:9], v[48:49]
	s_waitcnt vmcnt(9)
	v_pk_add_f32 v[2:3], v[2:3], v[50:51]
	v_pk_add_f32 v[4:5], v[4:5], v[52:53]
	s_waitcnt vmcnt(8)
	v_pk_add_f32 v[6:7], v[6:7], v[54:55]
	v_pk_add_f32 v[8:9], v[8:9], v[56:57]
	s_add_u32 s6, s44, 0x20000
	s_addc_u32 s7, s45, 0
	global_load_dwordx4 v[26:29], v176, s[6:7] nt
	global_load_dwordx4 v[30:33], v176, s[6:7] offset:1024 nt
	global_load_dwordx4 v[34:37], v177, s[6:7] nt
	global_load_dwordx4 v[38:41], v177, s[6:7] offset:1024 nt
	global_load_dwordx4 v[42:45], v178, s[6:7] nt
	global_load_dwordx4 v[46:49], v178, s[6:7] offset:1024 nt
	global_load_dwordx4 v[50:53], v179, s[6:7] nt
	global_load_dwordx4 v[54:57], v179, s[6:7] offset:1024 nt
	s_waitcnt vmcnt(15)
	v_pk_add_f32 v[2:3], v[2:3], v[140:141]
	v_pk_add_f32 v[4:5], v[4:5], v[142:143]
	s_waitcnt vmcnt(14)
	v_pk_add_f32 v[6:7], v[6:7], v[144:145]
	v_pk_add_f32 v[8:9], v[8:9], v[146:147]
	s_waitcnt vmcnt(13)
	v_pk_add_f32 v[2:3], v[2:3], v[148:149]
	v_pk_add_f32 v[4:5], v[4:5], v[150:151]
	s_waitcnt vmcnt(12)
	v_pk_add_f32 v[6:7], v[6:7], v[152:153]
	v_pk_add_f32 v[8:9], v[8:9], v[154:155]
	s_waitcnt vmcnt(11)
	v_pk_add_f32 v[2:3], v[2:3], v[156:157]
	v_pk_add_f32 v[4:5], v[4:5], v[158:159]
	s_waitcnt vmcnt(10)
	v_pk_add_f32 v[6:7], v[6:7], v[160:161]
	v_pk_add_f32 v[8:9], v[8:9], v[162:163]
	s_waitcnt vmcnt(9)
	v_pk_add_f32 v[2:3], v[2:3], v[164:165]
	v_pk_add_f32 v[4:5], v[4:5], v[166:167]
	s_waitcnt vmcnt(8)
	v_pk_add_f32 v[6:7], v[6:7], v[168:169]
	v_pk_add_f32 v[8:9], v[8:9], v[170:171]
	s_add_u32 s6, s44, 0x30000
	s_addc_u32 s7, s45, 0
	global_load_dwordx4 v[140:143], v176, s[6:7] nt
	global_load_dwordx4 v[144:147], v176, s[6:7] offset:1024 nt
	global_load_dwordx4 v[148:151], v177, s[6:7] nt
	global_load_dwordx4 v[152:155], v177, s[6:7] offset:1024 nt
	global_load_dwordx4 v[156:159], v178, s[6:7] nt
	global_load_dwordx4 v[160:163], v178, s[6:7] offset:1024 nt
	global_load_dwordx4 v[164:167], v179, s[6:7] nt
	global_load_dwordx4 v[168:171], v179, s[6:7] offset:1024 nt
	s_waitcnt vmcnt(15)
	v_pk_add_f32 v[2:3], v[2:3], v[26:27]
	v_pk_add_f32 v[4:5], v[4:5], v[28:29]
	s_waitcnt vmcnt(14)
	v_pk_add_f32 v[6:7], v[6:7], v[30:31]
	v_pk_add_f32 v[8:9], v[8:9], v[32:33]
	s_waitcnt vmcnt(13)
	v_pk_add_f32 v[2:3], v[2:3], v[34:35]
	v_pk_add_f32 v[4:5], v[4:5], v[36:37]
	s_waitcnt vmcnt(12)
	v_pk_add_f32 v[6:7], v[6:7], v[38:39]
	v_pk_add_f32 v[8:9], v[8:9], v[40:41]
	s_waitcnt vmcnt(11)
	v_pk_add_f32 v[2:3], v[2:3], v[42:43]
	v_pk_add_f32 v[4:5], v[4:5], v[44:45]
	s_waitcnt vmcnt(10)
	v_pk_add_f32 v[6:7], v[6:7], v[46:47]
	v_pk_add_f32 v[8:9], v[8:9], v[48:49]
	s_waitcnt vmcnt(9)
	v_pk_add_f32 v[2:3], v[2:3], v[50:51]
	v_pk_add_f32 v[4:5], v[4:5], v[52:53]
	s_waitcnt vmcnt(8)
	v_pk_add_f32 v[6:7], v[6:7], v[54:55]
	v_pk_add_f32 v[8:9], v[8:9], v[56:57]
	s_add_u32 s6, s44, 0x40000
	s_addc_u32 s7, s45, 0
	global_load_dwordx4 v[26:29], v176, s[6:7] nt
	global_load_dwordx4 v[30:33], v176, s[6:7] offset:1024 nt
	global_load_dwordx4 v[34:37], v177, s[6:7] nt
	global_load_dwordx4 v[38:41], v177, s[6:7] offset:1024 nt
	global_load_dwordx4 v[42:45], v178, s[6:7] nt
	global_load_dwordx4 v[46:49], v178, s[6:7] offset:1024 nt
	global_load_dwordx4 v[50:53], v179, s[6:7] nt
	global_load_dwordx4 v[54:57], v179, s[6:7] offset:1024 nt
	s_waitcnt vmcnt(15)
	v_pk_add_f32 v[2:3], v[2:3], v[140:141]
	v_pk_add_f32 v[4:5], v[4:5], v[142:143]
	s_waitcnt vmcnt(14)
	v_pk_add_f32 v[6:7], v[6:7], v[144:145]
	v_pk_add_f32 v[8:9], v[8:9], v[146:147]
	s_waitcnt vmcnt(13)
	v_pk_add_f32 v[2:3], v[2:3], v[148:149]
	v_pk_add_f32 v[4:5], v[4:5], v[150:151]
	s_waitcnt vmcnt(12)
	v_pk_add_f32 v[6:7], v[6:7], v[152:153]
	v_pk_add_f32 v[8:9], v[8:9], v[154:155]
	s_waitcnt vmcnt(11)
	v_pk_add_f32 v[2:3], v[2:3], v[156:157]
	v_pk_add_f32 v[4:5], v[4:5], v[158:159]
	s_waitcnt vmcnt(10)
; DI void kmean_item(const float* __restrict__ base, const int* __restrict__ pt, int b, int n, float* __restrict__ outp, char* sm) {
;     ...
;     for (int hf = 0; hf < 2; ++hf) {
;         const int pos0 = n * 256 + hf * 128;
;         const size_t r0 = pt ? (size_t)pt[b * 64 + (pos0 >> 7)] * 128 : (size_t)b * 8192 + pos0;
;         const float* rp = base + (r0 + w) * 1024 + lane * 4;
; #pragma unroll 4
;         for (int rr = 0; rr < 32; ++rr) {
;             a0 += __builtin_nontemporal_load((const f32x4*)(rp + (size_t)rr * 4096));
;             a1 += __builtin_nontemporal_load((const f32x4*)(rp + (size_t)rr * 4096 + 256));
;         }
;     }
;     *(f32x4*)(scr + w * 512 + lane * 4) = a0;
;     *(f32x4*)(scr + w * 512 + 256 + lane * 4) = a1;
;     __syncthreads();
; #pragma unroll
;     for (int j = 0; j < 2; ++j) {
;         const int col = t + 256 * j;
;         outp[col] = (scr[col] + scr[512 + col] + scr[1024 + col] + scr[1536 + col]) * (1.f / 256.f);
;     }
;     __syncthreads();
	v_pk_add_f32 v[6:7], v[6:7], v[160:161]
	v_pk_add_f32 v[8:9], v[8:9], v[162:163]
	s_waitcnt vmcnt(9)
	v_pk_add_f32 v[2:3], v[2:3], v[164:165]
	v_pk_add_f32 v[4:5], v[4:5], v[166:167]
	s_waitcnt vmcnt(8)
	v_pk_add_f32 v[6:7], v[6:7], v[168:169]
	v_pk_add_f32 v[8:9], v[8:9], v[170:171]
	s_add_u32 s6, s44, 0x50000
	s_addc_u32 s7, s45, 0
	global_load_dwordx4 v[140:143], v176, s[6:7] nt
	global_load_dwordx4 v[144:147], v176, s[6:7] offset:1024 nt
	global_load_dwordx4 v[148:151], v177, s[6:7] nt
	global_load_dwordx4 v[152:155], v177, s[6:7] offset:1024 nt
	global_load_dwordx4 v[156:159], v178, s[6:7] nt
	global_load_dwordx4 v[160:163], v178, s[6:7] offset:1024 nt
	global_load_dwordx4 v[164:167], v179, s[6:7] nt
	global_load_dwordx4 v[168:171], v179, s[6:7] offset:1024 nt
	s_waitcnt vmcnt(15)
	v_pk_add_f32 v[2:3], v[2:3], v[26:27]
	v_pk_add_f32 v[4:5], v[4:5], v[28:29]
	s_waitcnt vmcnt(14)
	v_pk_add_f32 v[6:7], v[6:7], v[30:31]
	v_pk_add_f32 v[8:9], v[8:9], v[32:33]
	s_waitcnt vmcnt(13)
	v_pk_add_f32 v[2:3], v[2:3], v[34:35]
	v_pk_add_f32 v[4:5], v[4:5], v[36:37]
	s_waitcnt vmcnt(12)
	v_pk_add_f32 v[6:7], v[6:7], v[38:39]
	v_pk_add_f32 v[8:9], v[8:9], v[40:41]
	s_waitcnt vmcnt(11)
	v_pk_add_f32 v[2:3], v[2:3], v[42:43]
	v_pk_add_f32 v[4:5], v[4:5], v[44:45]
	s_waitcnt vmcnt(10)
	v_pk_add_f32 v[6:7], v[6:7], v[46:47]
	v_pk_add_f32 v[8:9], v[8:9], v[48:49]
	s_waitcnt vmcnt(9)
	v_pk_add_f32 v[2:3], v[2:3], v[50:51]
	v_pk_add_f32 v[4:5], v[4:5], v[52:53]
	s_waitcnt vmcnt(8)
	v_pk_add_f32 v[6:7], v[6:7], v[54:55]
	v_pk_add_f32 v[8:9], v[8:9], v[56:57]
	s_add_u32 s6, s44, 0x60000
	s_addc_u32 s7, s45, 0
	global_load_dwordx4 v[26:29], v176, s[6:7] nt
	global_load_dwordx4 v[30:33], v176, s[6:7] offset:1024 nt
	global_load_dwordx4 v[34:37], v177, s[6:7] nt
	global_load_dwordx4 v[38:41], v177, s[6:7] offset:1024 nt
	global_load_dwordx4 v[42:45], v178, s[6:7] nt
	global_load_dwordx4 v[46:49], v178, s[6:7] offset:1024 nt
	global_load_dwordx4 v[50:53], v179, s[6:7] nt
	global_load_dwordx4 v[54:57], v179, s[6:7] offset:1024 nt
	s_waitcnt vmcnt(15)
	v_pk_add_f32 v[2:3], v[2:3], v[140:141]
	v_pk_add_f32 v[4:5], v[4:5], v[142:143]
	s_waitcnt vmcnt(14)
	v_pk_add_f32 v[6:7], v[6:7], v[144:145]
	v_pk_add_f32 v[8:9], v[8:9], v[146:147]
	s_waitcnt vmcnt(13)
	v_pk_add_f32 v[2:3], v[2:3], v[148:149]
	v_pk_add_f32 v[4:5], v[4:5], v[150:151]
	s_waitcnt vmcnt(12)
	v_pk_add_f32 v[6:7], v[6:7], v[152:153]
	v_pk_add_f32 v[8:9], v[8:9], v[154:155]
	s_waitcnt vmcnt(11)
	v_pk_add_f32 v[2:3], v[2:3], v[156:157]
	v_pk_add_f32 v[4:5], v[4:5], v[158:159]
	s_waitcnt vmcnt(10)
	v_pk_add_f32 v[6:7], v[6:7], v[160:161]
	v_pk_add_f32 v[8:9], v[8:9], v[162:163]
	s_waitcnt vmcnt(9)
	v_pk_add_f32 v[2:3], v[2:3], v[164:165]
	v_pk_add_f32 v[4:5], v[4:5], v[166:167]
	s_waitcnt vmcnt(8)
	v_pk_add_f32 v[6:7], v[6:7], v[168:169]
	v_pk_add_f32 v[8:9], v[8:9], v[170:171]
	s_add_u32 s6, s44, 0x70000
	s_addc_u32 s7, s45, 0
	global_load_dwordx4 v[140:143], v176, s[6:7] nt
	global_load_dwordx4 v[144:147], v176, s[6:7] offset:1024 nt
	global_load_dwordx4 v[148:151], v177, s[6:7] nt
	global_load_dwordx4 v[152:155], v177, s[6:7] offset:1024 nt
	global_load_dwordx4 v[156:159], v178, s[6:7] nt
	global_load_dwordx4 v[160:163], v178, s[6:7] offset:1024 nt
	global_load_dwordx4 v[164:167], v179, s[6:7] nt
	global_load_dwordx4 v[168:171], v179, s[6:7] offset:1024 nt
	s_waitcnt vmcnt(15)
	v_pk_add_f32 v[2:3], v[2:3], v[26:27]
	v_pk_add_f32 v[4:5], v[4:5], v[28:29]
	s_waitcnt vmcnt(14)
	v_pk_add_f32 v[6:7], v[6:7], v[30:31]
	v_pk_add_f32 v[8:9], v[8:9], v[32:33]
	s_waitcnt vmcnt(13)
	v_pk_add_f32 v[2:3], v[2:3], v[34:35]
	v_pk_add_f32 v[4:5], v[4:5], v[36:37]
	s_waitcnt vmcnt(12)
	v_pk_add_f32 v[6:7], v[6:7], v[38:39]
	v_pk_add_f32 v[8:9], v[8:9], v[40:41]
	s_waitcnt vmcnt(11)
	v_pk_add_f32 v[2:3], v[2:3], v[42:43]
	v_pk_add_f32 v[4:5], v[4:5], v[44:45]
	s_waitcnt vmcnt(10)
	v_pk_add_f32 v[6:7], v[6:7], v[46:47]
	v_pk_add_f32 v[8:9], v[8:9], v[48:49]
	s_waitcnt vmcnt(9)
	v_pk_add_f32 v[2:3], v[2:3], v[50:51]
	v_pk_add_f32 v[4:5], v[4:5], v[52:53]
	s_waitcnt vmcnt(8)
	v_pk_add_f32 v[6:7], v[6:7], v[54:55]
	v_pk_add_f32 v[8:9], v[8:9], v[56:57]
	s_waitcnt vmcnt(7)
	v_pk_add_f32 v[2:3], v[2:3], v[140:141]
	v_pk_add_f32 v[4:5], v[4:5], v[142:143]
	s_waitcnt vmcnt(6)
	v_pk_add_f32 v[6:7], v[6:7], v[144:145]
	v_pk_add_f32 v[8:9], v[8:9], v[146:147]
	s_waitcnt vmcnt(5)
	v_pk_add_f32 v[2:3], v[2:3], v[148:149]
	v_pk_add_f32 v[4:5], v[4:5], v[150:151]
	s_waitcnt vmcnt(4)
	v_pk_add_f32 v[6:7], v[6:7], v[152:153]
	v_pk_add_f32 v[8:9], v[8:9], v[154:155]
	s_waitcnt vmcnt(3)
	v_pk_add_f32 v[2:3], v[2:3], v[156:157]
	v_pk_add_f32 v[4:5], v[4:5], v[158:159]
	s_waitcnt vmcnt(2)
	v_pk_add_f32 v[6:7], v[6:7], v[160:161]
	v_pk_add_f32 v[8:9], v[8:9], v[162:163]
	s_waitcnt vmcnt(1)
	v_pk_add_f32 v[2:3], v[2:3], v[164:165]
	v_pk_add_f32 v[4:5], v[4:5], v[166:167]
	s_waitcnt vmcnt(0)
	v_pk_add_f32 v[6:7], v[6:7], v[168:169]
	v_pk_add_f32 v[8:9], v[8:9], v[170:171]
	v_lshlrev_b32_e32 v1, 11, v12
	v_add3_u32 v1, 0, v1, v18
	ds_write_b128 v1, v[2:5]
	ds_write_b128 v1, v[6:9] offset:1024
	v_lshl_add_u32 v1, v10, 2, 0
	s_waitcnt lgkmcnt(0)
	s_barrier
	ds_read2st64_b32 v[2:3], v1 offset1:4
	ds_read2st64_b32 v[4:5], v1 offset0:8 offset1:12
	ds_read2st64_b32 v[6:7], v1 offset0:16 offset1:20
	ds_read2st64_b32 v[8:9], v1 offset0:24 offset1:28
	s_mov_b32 s3, s75
	s_lshl_b64 s[2:3], s[2:3], 11
	s_waitcnt lgkmcnt(2)
	v_add_f32_e32 v1, v2, v4
	s_add_u32 s2, s33, s2
	s_waitcnt lgkmcnt(1)
	v_add_f32_e32 v1, v1, v6
	s_addc_u32 s3, s90, s3
	v_ashrrev_i32_e32 v11, 31, v10
	s_waitcnt lgkmcnt(0)
	v_add_f32_e32 v1, v1, v8
	v_mul_f32_e32 v1, 0x3b800000, v1
	v_lshl_add_u64 v[10:11], v[10:11], 2, s[2:3]
	global_store_dword v[10:11], v1, off
	v_add_f32_e32 v1, v3, v5
	v_add_f32_e32 v1, v1, v7
	v_add_f32_e32 v1, v1, v9
	v_mul_f32_e32 v1, 0x3b800000, v1
	global_store_dword v[10:11], v1, off offset:1024
	s_barrier

; DI void xcd_barrier(const XcdBarrier& b) {
;     asm volatile("s_waitcnt vmcnt(0)" ::: "memory");
;     __syncthreads();
;     if (threadIdx.x == 0) {
;         unsigned* bar = b.bar;
;         __builtin_amdgcn_s_waitcnt(0);
;         unsigned nloc = b.st[0], nx = b.st[1];
;         if (nloc == 0u) { xcd_barrier_complete(bar, b.x, nloc, nx); b.st[0] = nloc; b.st[1] = nx; }
; DI void ada_item(const Params& p, int item, char* sm) {
;     ...
;     for (int o = t; o < 34 * 16; o += 256) {
;         const int bb = o >> 4, c2 = o & 15;
;         float s = p.b_ada[col0 + c2];
; #pragma unroll
;         for (int g = 0; g < 16; ++g) s += scr[(g * 34 + bb) * 16 + c2];
;         mod[bb * 3072 + col0 + c2] = s;
;     }
.LBB0_112:
	global_load_dword v3, v[6:7], off
	v_ashrrev_i32_e32 v5, 4, v1
	s_movk_i32 s6, 0x11f
	v_add_u32_e32 v10, 0x100, v1
	v_cmp_lt_i32_e32 vcc, s6, v1
	v_lshl_add_u32 v11, v5, 6, v2
	s_movk_i32 s6, 0xc00
	v_mad_u64_u32 v[8:9], s[6:7], v5, s6, v[4:5]
	v_mov_b32_e32 v1, v10
	ds_read_b32 v5, v11
	ds_read_b32 v10, v11 offset:2176
	ds_read_b32 v12, v11 offset:4352
	ds_read_b32 v13, v11 offset:6528
	ds_read_b32 v14, v11 offset:8704
	ds_read_b32 v15, v11 offset:10880
	ds_read_b32 v16, v11 offset:13056
	ds_read_b32 v17, v11 offset:15232
	ds_read_b32 v18, v11 offset:17408
	ds_read_b32 v26, v11 offset:19584
	ds_read_b32 v27, v11 offset:21760
	ds_read_b32 v28, v11 offset:23936
	ds_read_b32 v29, v11 offset:26112
	ds_read_b32 v30, v11 offset:28288
	ds_read_b32 v31, v11 offset:30464
	ds_read_b32 v11, v11 offset:32640
	v_ashrrev_i32_e32 v9, 31, v8
	s_or_b64 s[4:5], vcc, s[4:5]
	v_lshl_add_u64 v[8:9], v[8:9], 2, s[72:73]
	s_waitcnt vmcnt(0) lgkmcnt(14)
	v_add_f32_e32 v3, v3, v5
	v_add_f32_e32 v3, v3, v10
	s_waitcnt lgkmcnt(13)
	v_add_f32_e32 v3, v3, v12
	s_waitcnt lgkmcnt(12)
	v_add_f32_e32 v3, v3, v13
	s_waitcnt lgkmcnt(11)
	v_add_f32_e32 v3, v3, v14
	s_waitcnt lgkmcnt(10)
	v_add_f32_e32 v3, v3, v15
	s_waitcnt lgkmcnt(9)
	v_add_f32_e32 v3, v3, v16
	s_waitcnt lgkmcnt(8)
	v_add_f32_e32 v3, v3, v17
	s_waitcnt lgkmcnt(7)
	v_add_f32_e32 v3, v3, v18
	s_waitcnt lgkmcnt(6)
	v_add_f32_e32 v3, v3, v26
	s_waitcnt lgkmcnt(5)
	v_add_f32_e32 v3, v3, v27
	s_waitcnt lgkmcnt(4)
	v_add_f32_e32 v3, v3, v28
	s_waitcnt lgkmcnt(3)
	v_add_f32_e32 v3, v3, v29
	s_waitcnt lgkmcnt(2)
	v_add_f32_e32 v3, v3, v30
	s_waitcnt lgkmcnt(1)
	v_add_f32_e32 v3, v3, v31
	s_waitcnt lgkmcnt(0)
	v_add_f32_e32 v3, v3, v11
	global_store_dword v[8:9], v3, off
	s_andn2_b64 exec, exec, s[4:5]
	s_cbranch_execnz .LBB0_112
	s_branch .LBB0_7
.LBB0_115:
	s_waitcnt vmcnt(0)
	s_waitcnt lgkmcnt(0)
	s_barrier
	s_and_saveexec_b64 s[2:3], s[14:15]
	s_cbranch_execz .LBB0_167
	s_add_i32 s4, 0, 0x103e0
	v_mov_b32_e32 v1, s4
	s_waitcnt vmcnt(0) expcnt(0) lgkmcnt(0)
	ds_read_b32 v3, v1
	s_add_i32 s4, 0, 0x103e4
	v_mov_b32_e32 v1, s4
	ds_read_b32 v1, v1
	s_waitcnt lgkmcnt(1)
	v_cmp_ne_u32_e32 vcc, 0, v3
	s_cbranch_vccnz .LBB0_131
	s_load_dwordx2 s[8:9], s[0:1], 0xb0
	s_load_dword s7, s[0:1], 0xb8
	s_add_u32 s4, s62, 0x1000
	s_addc_u32 s5, s63, 0
	s_add_u32 s6, s62, 0x1100
	s_waitcnt lgkmcnt(0)
	s_mul_i32 s22, s9, s8
	s_mul_i32 s22, s22, s7
	s_addc_u32 s7, s63, 0
	s_add_u32 s8, s62, 0x1200
	s_addc_u32 s9, s63, 0
	s_add_u32 s10, s62, 0x1300
	s_addc_u32 s11, s63, 0
	s_mov_b32 s23, 1
	v_mov_b32_e32 v17, 0
	s_branch .LBB0_119

; template <int MASK, bool NEAR, int PASS>
; DI void flash_tile(Flash& st, const bf16x8 (&qf)[4], const char* kbuf, const char* vbuf, int pos0, int qpos, bool on,
;                    const float* lut, float bfar, float* imp_row, float rinv) {
;     ...
;     for (int ks = 0; ks < 4; ++ks) {
;         const int ka = r * 128 + (((2 * ks + h) ^ ((r >> 1) & 7)) << 4);
;         const bf16x8 a0 = *(const bf16x8*)(kbuf + ka);
;         const bf16x8 a1 = *(const bf16x8*)(kbuf + 4096 + ka);
;     DI bool operator()(int pos0) const {
;         if (kind == 0) return qvalid;
;         if (kind == 1) { const int blk = pos0 >> 8; return qvalid && (blk == cur || ((lo >> blk) & 1ull)); }
;         const int j = pos0 >> 6;
;         if (j >= 128) return qvalid;
;         const unsigned long long x = j < 64 ? lo : hi;
;         return qvalid && ((x >> (j & 63)) & 1ull) != 0ull;
;     }
; template <int MASK, int PASS>
; DI void tile_step(Flash& st, const bf16x8 (&qf)[4], const char* kbuf, const char* vbuf, int pos0, int qpos, int qmin_w, int qmax_w,
;                   const OnFn& onfn, const float* lut, float bfar, float* imp_row, float rinv) {
;     const bool on = onfn(pos0);
;     if (__any(on)) {
;         bool farc;
;         if (MASK == 0) farc = pos0 + 63 + 113 <= qmin_w;
;         else if (MASK == 1) farc = (pos0 + 63 + 113 <= qmin_w) && (qmax_w - pos0 < 512);
;         else farc = 16 * (pos0 + 63) + 31 <= qmin_w;
;         if (farc) flash_tile<MASK, false, PASS>(st, qf, kbuf, vbuf, pos0, qpos, on, lut, bfar, imp_row, rinv);
;         else flash_tile<MASK, true, PASS>(st, qf, kbuf, vbuf, pos0, qpos, on, lut, bfar, imp_row, rinv);
; template <int MASK, int PASS>
; DI void run_tiles_b(Flash& st, const bf16x8 (&qf)[4], const BSrc& src, const int* list, int n, char* kvbuf, int qpos,
;                     int qmin_w, int qmax_w, const OnFn onfn, const float* lut, float bfar, float* imp_row, float rinv) {
;     TileRegsB RA, RB;
;     if (n > 0) tileb_issue(RA, src, list[0]);
;     if (n > 1) tileb_issue(RB, src, list[1]);
;     for (int i = 0; i < n; i += 2) {
;         {
;             tileb_store(RA, kvbuf, kvbuf + 8192);
;             __syncthreads();
;             const int pos0 = list[i];
;             if (i + 2 < n) tileb_issue(RA, src, list[i + 2]);
;             tile_step<MASK, PASS>(st, qf, kvbuf, kvbuf + 8192, pos0, qpos, qmin_w, qmax_w, onfn, lut, bfar, imp_row, rinv);
.LBB0_1364:
	v_add_u32_e32 v16, v161, v163
	v_add_u32_e32 v17, v161, v189
	v_mov_b32_e32 v2, s16
	ds_read_b32 v182, v2
	ds_read_b32 v183, v2 offset:8
	s_waitcnt vmcnt(3)
	ds_write_b128 v16, v[82:85]
	s_waitcnt vmcnt(2)
	ds_write_b128 v16, v[110:113] offset:4096
	s_waitcnt vmcnt(1)
	ds_write_b128 v17, v[114:117] offset:8192
	s_waitcnt vmcnt(0)
	ds_write_b128 v17, v[118:121] offset:12288
	s_waitcnt lgkmcnt(0)
	s_barrier
	v_add_u32_e32 v2, 0, v190
	ds_read_b128 v[50:53], v2
	ds_read_b128 v[138:141], v2 offset:4096
	v_add_u32_e32 v2, 0, v191
	ds_read_b128 v[150:153], v2
	ds_read_b128 v[12:15], v2 offset:4096
	v_add_u32_e32 v2, 0, v192
	ds_read_b128 v[146:149], v2
	ds_read_b128 v[8:11], v2 offset:4096
	v_add_u32_e32 v2, 0, v193
	ds_read_b128 v[142:145], v2
	ds_read_b128 v[4:7], v2 offset:4096
	s_add_i32 s21, s17, -1
	s_cmp_ge_i32 s21, s20
	v_readfirstlane_b32 s22, v182
	s_cbranch_scc1 .LBB0_1366
	v_add_u32_e32 v58, v183, v159
	v_min_i32_e32 v59, 0x1fdf, v58
	v_add_u32_e32 v59, 32, v59
	v_cmp_lt_i32_e32 vcc, s74, v58
	v_med3_i32 v56, v58, 0, v214
	v_lshlrev_b32_e32 v56, 7, v56
	v_mov_b32_e32 v57, 0
	v_cndmask_b32_e32 v58, 0, v59, vcc
	v_ashrrev_i32_e32 v59, 31, v58
	v_lshl_add_u64 v[60:61], v[172:173], 0, v[56:57]
	v_lshlrev_b64 v[58:59], 7, v[58:59]
	v_lshl_add_u64 v[62:63], v[172:173], 0, v[58:59]
	global_load_dwordx4 v[82:85], v[60:61], off
	global_load_dwordx4 v[110:113], v[62:63], off
	v_lshl_add_u64 v[60:61], v[176:177], 0, v[56:57]
	v_lshl_add_u64 v[58:59], v[176:177], 0, v[58:59]
	global_load_dwordx4 v[114:117], v[60:61], off
	global_load_dwordx4 v[118:121], v[58:59], off
.LBB0_1366:
	s_ashr_i32 s2, s22, 6
	s_cmpk_gt_i32 s2, 0x7f
	s_cselect_b64 vcc, -1, 0
	s_cmp_lt_i32 s2, 64
	s_cselect_b64 s[0:1], -1, 0
	v_cndmask_b32_e64 v65, v1, v157, s[0:1]
	v_cndmask_b32_e64 v64, v154, v174, s[0:1]
	v_lshrrev_b64 v[64:65], s2, v[64:65]
	v_and_b32_e32 v2, 1, v64
	v_cmp_eq_u32_e64 s[0:1], 1, v2
	s_and_b64 s[0:1], s[8:9], s[0:1]
	v_cndmask_b32_e64 v180, 0, 1, s[8:9]
	v_cndmask_b32_e64 v2, 0, 1, s[0:1]
	v_cndmask_b32_e32 v2, v2, v180, vcc
	v_and_b32_e32 v2, 1, v2
	v_cmp_eq_u32_e64 s[0:1], 1, v2
	v_cmp_ne_u32_e32 vcc, 0, v2
	s_cbranch_vccz .LBB0_1372
	s_add_i32 s2, s22, 0xb0
	v_cmp_le_i32_e32 vcc, s2, v226
	s_and_saveexec_b64 s[2:3], vcc
	s_xor_b64 s[2:3], exec, s[2:3]
	s_cbranch_execz .LBB0_1369
	s_waitcnt lgkmcnt(7)
	v_mfma_f32_32x32x16_bf16 v[66:81], v[50:53], v[94:97], 0
	s_waitcnt lgkmcnt(5)
	v_mfma_f32_32x32x16_bf16 v[66:81], v[150:153], v[98:101], v[66:81]
	v_mfma_f32_32x32x16_bf16 v[50:65], v[138:141], v[94:97], 0
	s_waitcnt lgkmcnt(3)
	v_mfma_f32_32x32x16_bf16 v[66:81], v[146:149], v[102:105], v[66:81]
	v_mfma_f32_32x32x16_bf16 v[50:65], v[12:15], v[98:101], v[50:65]
	s_waitcnt lgkmcnt(1)
	v_mfma_f32_32x32x16_bf16 v[66:81], v[142:145], v[106:109], v[66:81]
	v_mfma_f32_32x32x16_bf16 v[50:65], v[8:11], v[102:105], v[50:65]
	s_nop 10
	v_max_f32_e32 v2, v67, v67
	v_max_f32_e32 v12, v66, v66
	v_max_f32_e32 v2, v12, v2
	v_max3_f32 v2, v2, v68, v69
	v_max3_f32 v2, v2, v70, v71
	v_max3_f32 v2, v2, v72, v73
	v_max3_f32 v2, v2, v74, v75
	s_waitcnt lgkmcnt(0)
	v_mfma_f32_32x32x16_bf16 v[50:65], v[4:7], v[106:109], v[50:65]
	v_max3_f32 v2, v2, v76, v77
	v_max3_f32 v2, v2, v78, v79
	v_max3_f32 v2, v2, v80, v81
	s_nop 8
	v_max3_f32 v2, v2, v50, v51
	v_max3_f32 v2, v2, v52, v53
	v_max3_f32 v2, v2, v54, v55
	v_max3_f32 v2, v2, v56, v57
	v_max3_f32 v2, v2, v58, v59
	v_max3_f32 v2, v2, v60, v61
	v_max3_f32 v2, v2, v62, v63
	v_max3_f32 v2, v2, v64, v65
	v_fmamk_f32 v2, v2, 0x3e38aa3b, v225
	v_cndmask_b32_e64 v2, v215, v2, s[0:1]
	ds_bpermute_b32 v4, v175, v2
	s_waitcnt lgkmcnt(0)
; DI float fexp2(float x) { return __builtin_amdgcn_exp2f(x); }
; DI int opaque(int v) { asm volatile("" : "+v"(v)); return v; }
; template <int MASK, bool NEAR, int PASS>
; DI void flash_tile(Flash& st, const bf16x8 (&qf)[4], const char* kbuf, const char* vbuf, int pos0, int qpos, bool on,
;                    const float* lut, float bfar, float* imp_row, float rinv) {
;     ...
;     if (!NEAR) {
;         const float bc = MASK == 2 ? 0.f : bfar;
;         float mref;
;         if (PASS != 2) {
;             float mr = s[0][0];
; #pragma unroll
;             for (int i = 1; i < 16; ++i) mr = fmaxf(mr, s[0][i]);
; #pragma unroll
;             for (int i = 0; i < 16; ++i) mr = fmaxf(mr, s[1][i]);
;             float mx = on ? mr * c1 + bc : -1e30f;
;             mx = fmaxf(mx, __shfl_xor(mx, 32));
;             const float mnew = fmaxf(st.m, mx);
;             alpha = fexp2(st.m - mnew);
;             st.m = mnew;
;             mref = mnew;
;         } else mref = st.m;
;         float bm = on ? bc - mref : -1e30f;
;         if (PASS == 2) bm = on ? bm + __log2f(rinv) : -1e30f;
; #pragma unroll
;         for (int tt = 0; tt < 2; ++tt)
; #pragma unroll
;             for (int i = 0; i < 16; ++i) { const float pv = fexp2(s[tt][i] * c1 + bm); s[tt][i] = pv; rs += pv; }
;     ...
;     if (PASS != 2) {
;         rs += __shfl_xor(rs, 32);
;         st.l = st.l * alpha + rs;
;     }
;     f32x16 ia = zero16();
;     if (PASS != 1) {
;         if (PASS == 0) {
; #pragma unroll
;             for (int i = 0; i < 16; ++i) { st.o0[i] *= alpha; st.o1[i] *= alpha; }
;         }
;         const int G = lane >> 4, i16 = lane & 15, q = i16 >> 2, pp = i16 & 3;
;         const char* vb = vbuf + (4 * (G >> 1) + q) * 128 + (16 * (G & 1) + 4 * pp) * 2;
; #pragma unroll
;         for (int tt = 0; tt < 2; ++tt)
; #pragma unroll
;             for (int ss = 0; ss < 2; ++ss) {
;                 f32x4 pa = {s[tt][8 * ss], s[tt][8 * ss + 1], s[tt][8 * ss + 2], s[tt][8 * ss + 3]};
;                 f32x4 pb2 = {s[tt][8 * ss + 4], s[tt][8 * ss + 5], s[tt][8 * ss + 6], s[tt][8 * ss + 7]};
;                 const bf16x8 pfrag = cvt8(pa, pb2);
;                 const char* vk = vb + (32 * tt + 16 * ss) * 128;
;                 if (PASS == 2) {
;                     const int d = opaque((lane & 31) - h) - (8 * tt + 4 * ss);
;                     const unsigned one2 = 0x3F803F80u, oneh = 0x3F800000u;
	v_max3_f32 v138, v181, v2, v4
	v_sub_f32_e32 v4, v225, v138
	v_cndmask_b32_e64 v139, v215, v4, s[0:1]
	v_fmamk_f32 v4, v66, 0x3e38aa3b, v139
	v_exp_f32_e32 v8, v4
	v_fmamk_f32 v4, v67, 0x3e38aa3b, v139
	v_exp_f32_e32 v12, v4
	v_fmamk_f32 v4, v68, 0x3e38aa3b, v139
	v_exp_f32_e32 v9, v4
	v_fmamk_f32 v4, v69, 0x3e38aa3b, v139
	v_exp_f32_e32 v13, v4
	v_fmamk_f32 v4, v70, 0x3e38aa3b, v139
	v_exp_f32_e32 v10, v4
	v_fmamk_f32 v4, v71, 0x3e38aa3b, v139
	v_exp_f32_e32 v14, v4
	v_fmamk_f32 v4, v72, 0x3e38aa3b, v139
	v_exp_f32_e32 v11, v4
	v_fmamk_f32 v4, v73, 0x3e38aa3b, v139
	v_exp_f32_e32 v15, v4
	v_fmamk_f32 v4, v74, 0x3e38aa3b, v139
	v_exp_f32_e32 v66, v4
	v_fmamk_f32 v4, v75, 0x3e38aa3b, v139
	v_exp_f32_e32 v67, v4
	v_fmamk_f32 v4, v76, 0x3e38aa3b, v139
	v_exp_f32_e32 v68, v4
	v_fmamk_f32 v4, v77, 0x3e38aa3b, v139
	v_exp_f32_e32 v69, v4
	v_fmamk_f32 v4, v78, 0x3e38aa3b, v139
	v_exp_f32_e32 v70, v4
	v_fmamk_f32 v4, v79, 0x3e38aa3b, v139
	v_exp_f32_e32 v71, v4
	v_fmamk_f32 v4, v80, 0x3e38aa3b, v139
	v_exp_f32_e32 v72, v4
	v_add_f32_e32 v4, 0, v8
	v_add_f32_e32 v4, v12, v4
	v_add_f32_e32 v4, v9, v4
	v_add_f32_e32 v4, v13, v4
	v_add_f32_e32 v4, v10, v4
	v_add_f32_e32 v4, v14, v4
	v_add_f32_e32 v4, v11, v4
	v_add_f32_e32 v4, v15, v4
	v_add_f32_e32 v4, v66, v4
	v_add_f32_e32 v4, v67, v4
	v_fmamk_f32 v5, v81, 0x3e38aa3b, v139
	v_add_f32_e32 v4, v68, v4
	v_add_f32_e32 v4, v69, v4
	v_exp_f32_e32 v73, v5
	v_fmamk_f32 v5, v50, 0x3e38aa3b, v139
	v_add_f32_e32 v4, v70, v4
	v_exp_f32_e32 v50, v5
	v_fmamk_f32 v5, v51, 0x3e38aa3b, v139
	v_add_f32_e32 v4, v71, v4
	v_exp_f32_e32 v51, v5
	v_fmamk_f32 v5, v52, 0x3e38aa3b, v139
	v_add_f32_e32 v4, v72, v4
	v_exp_f32_e32 v52, v5
	v_fmamk_f32 v5, v53, 0x3e38aa3b, v139
	v_add_f32_e32 v4, v73, v4
	v_exp_f32_e32 v53, v5
	v_fmamk_f32 v5, v54, 0x3e38aa3b, v139
	v_add_f32_e32 v4, v50, v4
	v_exp_f32_e32 v54, v5
	v_fmamk_f32 v5, v55, 0x3e38aa3b, v139
	v_add_f32_e32 v4, v51, v4
	v_exp_f32_e32 v55, v5
	v_fmamk_f32 v5, v56, 0x3e38aa3b, v139
	v_add_f32_e32 v4, v52, v4
	v_exp_f32_e32 v56, v5
	v_fmamk_f32 v5, v57, 0x3e38aa3b, v139
	v_add_f32_e32 v4, v53, v4
	v_exp_f32_e32 v57, v5
	v_fmamk_f32 v5, v58, 0x3e38aa3b, v139
	v_add_f32_e32 v4, v54, v4
	v_exp_f32_e32 v58, v5
	v_fmamk_f32 v5, v59, 0x3e38aa3b, v139
	v_add_f32_e32 v4, v55, v4
	v_exp_f32_e32 v59, v5
	v_fmamk_f32 v5, v60, 0x3e38aa3b, v139
	v_add_f32_e32 v4, v56, v4
	v_exp_f32_e32 v60, v5
	v_add_f32_e32 v4, v57, v4
	v_add_f32_e32 v4, v58, v4
	v_add_f32_e32 v4, v59, v4
	v_sub_f32_e32 v2, v181, v138
	v_add_f32_e32 v74, v60, v4
	v_fmamk_f32 v4, v61, 0x3e38aa3b, v139
	v_exp_f32_e32 v2, v2
	v_exp_f32_e32 v61, v4
	ds_read_b64_tr_b16 v[4:5], v194 offset:8192
	ds_read_b64_tr_b16 v[6:7], v194 offset:9216
	v_cvt_pk_bf16_f32 v11, v11, v15
	v_cvt_pk_bf16_f32 v10, v10, v14
	v_cvt_pk_bf16_f32 v9, v9, v13
	v_cvt_pk_bf16_f32 v8, v8, v12
	ds_read_b64_tr_b16 v[14:15], v194 offset:9280
	ds_read_b64_tr_b16 v[12:13], v194 offset:8256
	v_pk_mul_f32 v[48:49], v[48:49], v[2:3] op_sel_hi:[1,0]
	v_pk_mul_f32 v[46:47], v[46:47], v[2:3] op_sel_hi:[1,0]
	v_pk_mul_f32 v[44:45], v[44:45], v[2:3] op_sel_hi:[1,0]
	v_pk_mul_f32 v[42:43], v[42:43], v[2:3] op_sel_hi:[1,0]
	v_pk_mul_f32 v[40:41], v[40:41], v[2:3] op_sel_hi:[1,0]
	v_pk_mul_f32 v[38:39], v[38:39], v[2:3] op_sel_hi:[1,0]
	v_pk_mul_f32 v[36:37], v[36:37], v[2:3] op_sel_hi:[1,0]
	v_pk_mul_f32 v[34:35], v[34:35], v[2:3] op_sel_hi:[1,0]
	v_pk_mul_f32 v[32:33], v[32:33], v[2:3] op_sel_hi:[1,0]
	v_pk_mul_f32 v[30:31], v[30:31], v[2:3] op_sel_hi:[1,0]
	v_pk_mul_f32 v[28:29], v[28:29], v[2:3] op_sel_hi:[1,0]
	v_pk_mul_f32 v[26:27], v[26:27], v[2:3] op_sel_hi:[1,0]
	v_pk_mul_f32 v[24:25], v[24:25], v[2:3] op_sel_hi:[1,0]
	v_pk_mul_f32 v[22:23], v[22:23], v[2:3] op_sel_hi:[1,0]
	v_pk_mul_f32 v[20:21], v[20:21], v[2:3] op_sel_hi:[1,0]
	v_pk_mul_f32 v[18:19], v[18:19], v[2:3] op_sel_hi:[1,0]
	s_waitcnt lgkmcnt(2)
	v_mfma_f32_32x32x16_bf16 v[34:49], v[4:7], v[8:11], v[34:49]
	ds_read_b64_tr_b16 v[4:5], v194 offset:10240
	ds_read_b64_tr_b16 v[6:7], v194 offset:11264
	v_fmamk_f32 v64, v64, 0x3e38aa3b, v139
	v_exp_f32_e32 v64, v64
	v_add_f32_e32 v74, v61, v74
	v_mov_b32_e32 v181, v138
	s_waitcnt lgkmcnt(2)
	v_mfma_f32_32x32x16_bf16 v[18:33], v[12:15], v[8:11], v[18:33]
	ds_read_b64_tr_b16 v[14:15], v194 offset:11328
	ds_read_b64_tr_b16 v[12:13], v194 offset:10304
	v_cvt_pk_bf16_f32 v11, v72, v73
	v_cvt_pk_bf16_f32 v10, v70, v71
	v_cvt_pk_bf16_f32 v9, v68, v69
	v_cvt_pk_bf16_f32 v8, v66, v67
	s_waitcnt lgkmcnt(2)
	s_nop 0
	v_mfma_f32_32x32x16_bf16 v[34:49], v[4:7], v[8:11], v[34:49]
	v_fmamk_f32 v4, v62, 0x3e38aa3b, v139
	v_exp_f32_e32 v62, v4
	v_fmamk_f32 v4, v63, 0x3e38aa3b, v139
	v_exp_f32_e32 v63, v4
	ds_read_b64_tr_b16 v[4:5], v194 offset:12288
	ds_read_b64_tr_b16 v[6:7], v194 offset:13312
	v_fmac_f32_e32 v139, 0x3e38aa3b, v65
	s_waitcnt lgkmcnt(2)
	v_mfma_f32_32x32x16_bf16 v[18:33], v[12:15], v[8:11], v[18:33]
	ds_read_b64_tr_b16 v[14:15], v194 offset:13376
	ds_read_b64_tr_b16 v[12:13], v194 offset:12352
	v_cvt_pk_bf16_f32 v11, v56, v57
	v_cvt_pk_bf16_f32 v10, v54, v55
	v_cvt_pk_bf16_f32 v9, v52, v53
	v_cvt_pk_bf16_f32 v8, v50, v51
	v_exp_f32_e32 v51, v139
	s_waitcnt lgkmcnt(2)
	v_mfma_f32_32x32x16_bf16 v[34:49], v[4:7], v[8:11], v[34:49]
	v_add_f32_e32 v4, v62, v74
	v_add_f32_e32 v4, v63, v4
	v_add_f32_e32 v50, v64, v4
	ds_read_b64_tr_b16 v[4:5], v194 offset:14336
	ds_read_b64_tr_b16 v[6:7], v194 offset:15360
	v_add_f32_e32 v50, v51, v50
	s_waitcnt lgkmcnt(2)
	v_mfma_f32_32x32x16_bf16 v[18:33], v[12:15], v[8:11], v[18:33]
	ds_read_b64_tr_b16 v[14:15], v194 offset:15424
	ds_read_b64_tr_b16 v[12:13], v194 offset:14400
	v_cvt_pk_bf16_f32 v11, v64, v51
	v_cvt_pk_bf16_f32 v10, v62, v63
	v_cvt_pk_bf16_f32 v9, v60, v61
	v_cvt_pk_bf16_f32 v8, v58, v59
	s_waitcnt lgkmcnt(2)
	s_nop 0
	v_mfma_f32_32x32x16_bf16 v[34:49], v[4:7], v[8:11], v[34:49]
	ds_bpermute_b32 v4, v175, v50
	s_waitcnt lgkmcnt(0)
	v_add_f32_e32 v4, v50, v4
	v_fmac_f32_e32 v4, v169, v2
	v_mfma_f32_32x32x16_bf16 v[18:33], v[12:15], v[8:11], v[18:33]
	v_mov_b32_e32 v169, v4

; template <int MASK, bool NEAR, int PASS>
; DI void flash_tile(Flash& st, const bf16x8 (&qf)[4], const char* kbuf, const char* vbuf, int pos0, int qpos, bool on,
;                    const float* lut, float bfar, float* imp_row, float rinv) {
;     ...
;     for (int ks = 0; ks < 4; ++ks) {
;         const int ka = r * 128 + (((2 * ks + h) ^ ((r >> 1) & 7)) << 4);
;         const bf16x8 a0 = *(const bf16x8*)(kbuf + ka);
;         const bf16x8 a1 = *(const bf16x8*)(kbuf + 4096 + ka);
;         s[0] = mfma32(a0, qf[ks], s[0]);
;         s[1] = mfma32(a1, qf[ks], s[1]);
;     }
;     DI bool operator()(int pos0) const {
;         if (kind == 0) return qvalid;
;         if (kind == 1) { const int blk = pos0 >> 8; return qvalid && (blk == cur || ((lo >> blk) & 1ull)); }
;         const int j = pos0 >> 6;
;         if (j >= 128) return qvalid;
;         const unsigned long long x = j < 64 ? lo : hi;
;         return qvalid && ((x >> (j & 63)) & 1ull) != 0ull;
;     }
; template <int MASK, int PASS>
; DI void tile_step(Flash& st, const bf16x8 (&qf)[4], const char* kbuf, const char* vbuf, int pos0, int qpos, int qmin_w, int qmax_w,
;                   const OnFn& onfn, const float* lut, float bfar, float* imp_row, float rinv) {
;     const bool on = onfn(pos0);
;     if (__any(on)) {
;         bool farc;
;         if (MASK == 0) farc = pos0 + 63 + 113 <= qmin_w;
;         else if (MASK == 1) farc = (pos0 + 63 + 113 <= qmin_w) && (qmax_w - pos0 < 512);
;         else farc = 16 * (pos0 + 63) + 31 <= qmin_w;
;         if (farc) flash_tile<MASK, false, PASS>(st, qf, kbuf, vbuf, pos0, qpos, on, lut, bfar, imp_row, rinv);
;         else flash_tile<MASK, true, PASS>(st, qf, kbuf, vbuf, pos0, qpos, on, lut, bfar, imp_row, rinv);
; template <int MASK, int PASS>
; DI void run_tiles_b(Flash& st, const bf16x8 (&qf)[4], const BSrc& src, const int* list, int n, char* kvbuf, int qpos,
;                     int qmin_w, int qmax_w, const OnFn onfn, const float* lut, float bfar, float* imp_row, float rinv) {
;     ...
;         if (i + 1 < n) {
;             tileb_store(RB, kvbuf + 16384, kvbuf + 24576);
;             __syncthreads();
;             const int pos0 = list[i + 1];
;             if (i + 3 < n) tileb_issue(RB, src, list[i + 3]);
;             tile_step<MASK, PASS>(st, qf, kvbuf + 16384, kvbuf + 24576, pos0, qpos, qmin_w, qmax_w, onfn, lut, bfar, imp_row, rinv);
.LBB0_1372:
	s_add_i32 s0, s17, -2
	s_cmp_ge_i32 s0, s20
	s_cbranch_scc1 .LBB0_1363
	v_mov_b32_e32 v2, s16
	ds_read_b32 v182, v2 offset:4
	ds_read_b32 v183, v2 offset:12
	ds_write_b128 v16, v[122:125] offset:16384
	ds_write_b128 v16, v[126:129] offset:20480
	ds_write_b128 v17, v[130:133] offset:24576
	ds_write_b128 v17, v[134:137] offset:28672
	s_waitcnt lgkmcnt(0)
	s_barrier
	v_add_u32_e32 v2, 0, v190
	ds_read_b128 v[50:53], v2 offset:16384
	ds_read_b128 v[138:141], v2 offset:20480
	v_add_u32_e32 v2, 0, v191
	ds_read_b128 v[150:153], v2 offset:16384
	ds_read_b128 v[12:15], v2 offset:20480
	v_add_u32_e32 v2, 0, v192
	ds_read_b128 v[146:149], v2 offset:16384
	ds_read_b128 v[8:11], v2 offset:20480
	v_add_u32_e32 v2, 0, v193
	ds_read_b128 v[142:145], v2 offset:16384
	ds_read_b128 v[4:7], v2 offset:20480
	s_cmp_ge_i32 s17, s20
	v_readfirstlane_b32 s22, v182
	s_cbranch_scc1 .LBB0_1375
	v_add_u32_e32 v58, v183, v159
	v_min_i32_e32 v59, 0x1fdf, v58
	v_add_u32_e32 v59, 32, v59
	v_cmp_lt_i32_e32 vcc, s74, v58
	v_med3_i32 v56, v58, 0, v214
	v_lshlrev_b32_e32 v56, 7, v56
	v_mov_b32_e32 v57, 0
	v_cndmask_b32_e32 v58, 0, v59, vcc
	v_ashrrev_i32_e32 v59, 31, v58
	v_lshl_add_u64 v[60:61], v[172:173], 0, v[56:57]
	v_lshlrev_b64 v[58:59], 7, v[58:59]
	v_lshl_add_u64 v[62:63], v[172:173], 0, v[58:59]
	global_load_dwordx4 v[122:125], v[60:61], off
	global_load_dwordx4 v[126:129], v[62:63], off
	v_lshl_add_u64 v[60:61], v[176:177], 0, v[56:57]
	v_lshl_add_u64 v[58:59], v[176:177], 0, v[58:59]
	global_load_dwordx4 v[130:133], v[60:61], off
	global_load_dwordx4 v[134:137], v[58:59], off
.LBB0_1375:
	s_ashr_i32 s2, s22, 6
	s_cmpk_gt_i32 s2, 0x7f
	s_cselect_b64 vcc, -1, 0
	s_cmp_lt_i32 s2, 64
	s_cselect_b64 s[0:1], -1, 0
	v_cndmask_b32_e64 v65, v1, v157, s[0:1]
	v_cndmask_b32_e64 v64, v154, v174, s[0:1]
	v_lshrrev_b64 v[64:65], s2, v[64:65]
	v_and_b32_e32 v2, 1, v64
	v_cmp_eq_u32_e64 s[0:1], 1, v2
	s_and_b64 s[0:1], s[8:9], s[0:1]
	s_nop 0
	v_cndmask_b32_e64 v2, 0, 1, s[0:1]
	v_cndmask_b32_e32 v2, v2, v180, vcc
	v_and_b32_e32 v2, 1, v2
	v_cmp_eq_u32_e64 s[0:1], 1, v2
	v_cmp_ne_u32_e32 vcc, 0, v2
	s_cbranch_vccz .LBB0_1363
	s_add_i32 s2, s22, 0xb0
	v_cmp_le_i32_e32 vcc, s2, v226
	s_and_saveexec_b64 s[2:3], vcc
	s_xor_b64 s[2:3], exec, s[2:3]
	s_cbranch_execz .LBB0_1378
	s_waitcnt lgkmcnt(7)
	v_mfma_f32_32x32x16_bf16 v[66:81], v[50:53], v[94:97], 0
	s_waitcnt lgkmcnt(5)
	v_mfma_f32_32x32x16_bf16 v[66:81], v[150:153], v[98:101], v[66:81]
	v_mfma_f32_32x32x16_bf16 v[50:65], v[138:141], v[94:97], 0
	s_waitcnt lgkmcnt(3)
	v_mfma_f32_32x32x16_bf16 v[66:81], v[146:149], v[102:105], v[66:81]
	v_mfma_f32_32x32x16_bf16 v[50:65], v[12:15], v[98:101], v[50:65]
	s_waitcnt lgkmcnt(1)
	v_mfma_f32_32x32x16_bf16 v[66:81], v[142:145], v[106:109], v[66:81]
	v_mfma_f32_32x32x16_bf16 v[50:65], v[8:11], v[102:105], v[50:65]
	s_nop 10
	v_max_f32_e32 v2, v67, v67
	v_max_f32_e32 v12, v66, v66
	v_max_f32_e32 v2, v12, v2
	v_max3_f32 v2, v2, v68, v69
	v_max3_f32 v2, v2, v70, v71
	v_max3_f32 v2, v2, v72, v73
	v_max3_f32 v2, v2, v74, v75
	s_waitcnt lgkmcnt(0)
	v_mfma_f32_32x32x16_bf16 v[50:65], v[4:7], v[106:109], v[50:65]
	v_max3_f32 v2, v2, v76, v77
	v_max3_f32 v2, v2, v78, v79
	v_max3_f32 v2, v2, v80, v81
	s_nop 8
	v_max3_f32 v2, v2, v50, v51
	v_max3_f32 v2, v2, v52, v53
	v_max3_f32 v2, v2, v54, v55
	v_max3_f32 v2, v2, v56, v57
	v_max3_f32 v2, v2, v58, v59
	v_max3_f32 v2, v2, v60, v61
	v_max3_f32 v2, v2, v62, v63
	v_max3_f32 v2, v2, v64, v65
	v_fmamk_f32 v2, v2, 0x3e38aa3b, v225
	v_cndmask_b32_e64 v2, v215, v2, s[0:1]
	ds_bpermute_b32 v4, v175, v2
	s_waitcnt lgkmcnt(0)
; DI float fexp2(float x) { return __builtin_amdgcn_exp2f(x); }
; DI int opaque(int v) { asm volatile("" : "+v"(v)); return v; }
; template <int MASK, bool NEAR, int PASS>
; DI void flash_tile(Flash& st, const bf16x8 (&qf)[4], const char* kbuf, const char* vbuf, int pos0, int qpos, bool on,
;                    const float* lut, float bfar, float* imp_row, float rinv) {
;     ...
;     if (!NEAR) {
;         const float bc = MASK == 2 ? 0.f : bfar;
;         float mref;
;         if (PASS != 2) {
;             float mr = s[0][0];
; #pragma unroll
;             for (int i = 1; i < 16; ++i) mr = fmaxf(mr, s[0][i]);
; #pragma unroll
;             for (int i = 0; i < 16; ++i) mr = fmaxf(mr, s[1][i]);
;             float mx = on ? mr * c1 + bc : -1e30f;
;             mx = fmaxf(mx, __shfl_xor(mx, 32));
;             const float mnew = fmaxf(st.m, mx);
;             alpha = fexp2(st.m - mnew);
;             st.m = mnew;
;             mref = mnew;
;         } else mref = st.m;
;         float bm = on ? bc - mref : -1e30f;
;         if (PASS == 2) bm = on ? bm + __log2f(rinv) : -1e30f;
; #pragma unroll
;         for (int tt = 0; tt < 2; ++tt)
; #pragma unroll
;             for (int i = 0; i < 16; ++i) { const float pv = fexp2(s[tt][i] * c1 + bm); s[tt][i] = pv; rs += pv; }
;     ...
;     if (PASS != 2) {
;         rs += __shfl_xor(rs, 32);
;         st.l = st.l * alpha + rs;
;     }
;     f32x16 ia = zero16();
;     if (PASS != 1) {
;         if (PASS == 0) {
; #pragma unroll
;             for (int i = 0; i < 16; ++i) { st.o0[i] *= alpha; st.o1[i] *= alpha; }
;         }
;         const int G = lane >> 4, i16 = lane & 15, q = i16 >> 2, pp = i16 & 3;
;         const char* vb = vbuf + (4 * (G >> 1) + q) * 128 + (16 * (G & 1) + 4 * pp) * 2;
; #pragma unroll
;         for (int tt = 0; tt < 2; ++tt)
; #pragma unroll
;             for (int ss = 0; ss < 2; ++ss) {
;                 f32x4 pa = {s[tt][8 * ss], s[tt][8 * ss + 1], s[tt][8 * ss + 2], s[tt][8 * ss + 3]};
;                 f32x4 pb2 = {s[tt][8 * ss + 4], s[tt][8 * ss + 5], s[tt][8 * ss + 6], s[tt][8 * ss + 7]};
;                 const bf16x8 pfrag = cvt8(pa, pb2);
;                 const char* vk = vb + (32 * tt + 16 * ss) * 128;
;                 if (PASS == 2) {
;                     const int d = opaque((lane & 31) - h) - (8 * tt + 4 * ss);
;                     const unsigned one2 = 0x3F803F80u, oneh = 0x3F800000u;
	v_max3_f32 v16, v181, v2, v4
	v_sub_f32_e32 v4, v225, v16
	v_cndmask_b32_e64 v17, v215, v4, s[0:1]
	v_fmamk_f32 v4, v66, 0x3e38aa3b, v17
	v_exp_f32_e32 v8, v4
	v_fmamk_f32 v4, v67, 0x3e38aa3b, v17
	v_exp_f32_e32 v12, v4
	v_fmamk_f32 v4, v68, 0x3e38aa3b, v17
	v_exp_f32_e32 v9, v4
	v_fmamk_f32 v4, v69, 0x3e38aa3b, v17
	v_exp_f32_e32 v13, v4
	v_fmamk_f32 v4, v70, 0x3e38aa3b, v17
	v_exp_f32_e32 v10, v4
	v_fmamk_f32 v4, v71, 0x3e38aa3b, v17
	v_exp_f32_e32 v14, v4
	v_fmamk_f32 v4, v72, 0x3e38aa3b, v17
	v_exp_f32_e32 v11, v4
	v_fmamk_f32 v4, v73, 0x3e38aa3b, v17
	v_exp_f32_e32 v15, v4
	v_fmamk_f32 v4, v74, 0x3e38aa3b, v17
	v_exp_f32_e32 v66, v4
	v_fmamk_f32 v4, v75, 0x3e38aa3b, v17
	v_exp_f32_e32 v67, v4
	v_fmamk_f32 v4, v76, 0x3e38aa3b, v17
	v_exp_f32_e32 v68, v4
	v_fmamk_f32 v4, v77, 0x3e38aa3b, v17
	v_exp_f32_e32 v69, v4
	v_fmamk_f32 v4, v78, 0x3e38aa3b, v17
	v_exp_f32_e32 v70, v4
	v_fmamk_f32 v4, v79, 0x3e38aa3b, v17
	v_exp_f32_e32 v71, v4
	v_fmamk_f32 v4, v80, 0x3e38aa3b, v17
	v_exp_f32_e32 v72, v4
	v_add_f32_e32 v4, 0, v8
	v_add_f32_e32 v4, v12, v4
	v_add_f32_e32 v4, v9, v4
	v_add_f32_e32 v4, v13, v4
	v_add_f32_e32 v4, v10, v4
	v_add_f32_e32 v4, v14, v4
	v_add_f32_e32 v4, v11, v4
	v_add_f32_e32 v4, v15, v4
	v_add_f32_e32 v4, v66, v4
	v_add_f32_e32 v4, v67, v4
	v_fmamk_f32 v5, v81, 0x3e38aa3b, v17
	v_add_f32_e32 v4, v68, v4
	v_add_f32_e32 v4, v69, v4
	v_exp_f32_e32 v73, v5
	v_fmamk_f32 v5, v50, 0x3e38aa3b, v17
	v_add_f32_e32 v4, v70, v4
	v_exp_f32_e32 v50, v5
	v_fmamk_f32 v5, v51, 0x3e38aa3b, v17
	v_add_f32_e32 v4, v71, v4
	v_exp_f32_e32 v51, v5
	v_fmamk_f32 v5, v52, 0x3e38aa3b, v17
	v_add_f32_e32 v4, v72, v4
	v_exp_f32_e32 v52, v5
	v_fmamk_f32 v5, v53, 0x3e38aa3b, v17
	v_add_f32_e32 v4, v73, v4
	v_exp_f32_e32 v53, v5
	v_fmamk_f32 v5, v54, 0x3e38aa3b, v17
	v_add_f32_e32 v4, v50, v4
	v_exp_f32_e32 v54, v5
	v_fmamk_f32 v5, v55, 0x3e38aa3b, v17
	v_add_f32_e32 v4, v51, v4
	v_exp_f32_e32 v55, v5
	v_fmamk_f32 v5, v56, 0x3e38aa3b, v17
	v_add_f32_e32 v4, v52, v4
	v_exp_f32_e32 v56, v5
	v_fmamk_f32 v5, v57, 0x3e38aa3b, v17
	v_add_f32_e32 v4, v53, v4
	v_exp_f32_e32 v57, v5
	v_fmamk_f32 v5, v58, 0x3e38aa3b, v17
	v_add_f32_e32 v4, v54, v4
	v_exp_f32_e32 v58, v5
	v_fmamk_f32 v5, v59, 0x3e38aa3b, v17
	v_add_f32_e32 v4, v55, v4
	v_exp_f32_e32 v59, v5
	v_fmamk_f32 v5, v60, 0x3e38aa3b, v17
	v_add_f32_e32 v4, v56, v4
	v_exp_f32_e32 v60, v5
	v_add_f32_e32 v4, v57, v4
	v_add_f32_e32 v4, v58, v4
	v_add_f32_e32 v4, v59, v4
	v_sub_f32_e32 v2, v181, v16
	v_add_f32_e32 v74, v60, v4
	v_fmamk_f32 v4, v61, 0x3e38aa3b, v17
	v_exp_f32_e32 v2, v2
	v_exp_f32_e32 v61, v4
	ds_read_b64_tr_b16 v[4:5], v194 offset:24576
	ds_read_b64_tr_b16 v[6:7], v194 offset:25600
	v_cvt_pk_bf16_f32 v11, v11, v15
	v_cvt_pk_bf16_f32 v10, v10, v14
	v_cvt_pk_bf16_f32 v9, v9, v13
	v_cvt_pk_bf16_f32 v8, v8, v12
	ds_read_b64_tr_b16 v[14:15], v194 offset:25664
	ds_read_b64_tr_b16 v[12:13], v194 offset:24640
	v_pk_mul_f32 v[48:49], v[48:49], v[2:3] op_sel_hi:[1,0]
	v_pk_mul_f32 v[46:47], v[46:47], v[2:3] op_sel_hi:[1,0]
	v_pk_mul_f32 v[44:45], v[44:45], v[2:3] op_sel_hi:[1,0]
	v_pk_mul_f32 v[42:43], v[42:43], v[2:3] op_sel_hi:[1,0]
	v_pk_mul_f32 v[40:41], v[40:41], v[2:3] op_sel_hi:[1,0]
	v_pk_mul_f32 v[38:39], v[38:39], v[2:3] op_sel_hi:[1,0]
	v_pk_mul_f32 v[36:37], v[36:37], v[2:3] op_sel_hi:[1,0]
	v_pk_mul_f32 v[34:35], v[34:35], v[2:3] op_sel_hi:[1,0]
	v_pk_mul_f32 v[32:33], v[32:33], v[2:3] op_sel_hi:[1,0]
	v_pk_mul_f32 v[30:31], v[30:31], v[2:3] op_sel_hi:[1,0]
	v_pk_mul_f32 v[28:29], v[28:29], v[2:3] op_sel_hi:[1,0]
	v_pk_mul_f32 v[26:27], v[26:27], v[2:3] op_sel_hi:[1,0]
	v_pk_mul_f32 v[24:25], v[24:25], v[2:3] op_sel_hi:[1,0]
	v_pk_mul_f32 v[22:23], v[22:23], v[2:3] op_sel_hi:[1,0]
	v_pk_mul_f32 v[20:21], v[20:21], v[2:3] op_sel_hi:[1,0]
	v_pk_mul_f32 v[18:19], v[18:19], v[2:3] op_sel_hi:[1,0]
	s_waitcnt lgkmcnt(2)
	v_mfma_f32_32x32x16_bf16 v[34:49], v[4:7], v[8:11], v[34:49]
	ds_read_b64_tr_b16 v[4:5], v194 offset:26624
	ds_read_b64_tr_b16 v[6:7], v194 offset:27648
	v_fmamk_f32 v64, v64, 0x3e38aa3b, v17
	v_exp_f32_e32 v64, v64
	v_add_f32_e32 v74, v61, v74
	v_mov_b32_e32 v181, v16
	s_waitcnt lgkmcnt(2)
	v_mfma_f32_32x32x16_bf16 v[18:33], v[12:15], v[8:11], v[18:33]
	ds_read_b64_tr_b16 v[14:15], v194 offset:27712
	ds_read_b64_tr_b16 v[12:13], v194 offset:26688
	v_cvt_pk_bf16_f32 v11, v72, v73
	v_cvt_pk_bf16_f32 v10, v70, v71
	v_cvt_pk_bf16_f32 v9, v68, v69
	v_cvt_pk_bf16_f32 v8, v66, v67
	s_waitcnt lgkmcnt(2)
	s_nop 0
	v_mfma_f32_32x32x16_bf16 v[34:49], v[4:7], v[8:11], v[34:49]
	v_fmamk_f32 v4, v62, 0x3e38aa3b, v17
	v_exp_f32_e32 v62, v4
	v_fmamk_f32 v4, v63, 0x3e38aa3b, v17
	v_exp_f32_e32 v63, v4
	ds_read_b64_tr_b16 v[4:5], v194 offset:28672
	ds_read_b64_tr_b16 v[6:7], v194 offset:29696
	v_fmac_f32_e32 v17, 0x3e38aa3b, v65
	v_exp_f32_e32 v17, v17
	s_waitcnt lgkmcnt(2)
	v_mfma_f32_32x32x16_bf16 v[18:33], v[12:15], v[8:11], v[18:33]
	ds_read_b64_tr_b16 v[14:15], v194 offset:29760
	ds_read_b64_tr_b16 v[12:13], v194 offset:28736
	v_cvt_pk_bf16_f32 v11, v56, v57
	v_cvt_pk_bf16_f32 v10, v54, v55
	v_cvt_pk_bf16_f32 v9, v52, v53
	v_cvt_pk_bf16_f32 v8, v50, v51
	s_waitcnt lgkmcnt(2)
	s_nop 0
	v_mfma_f32_32x32x16_bf16 v[34:49], v[4:7], v[8:11], v[34:49]
	v_add_f32_e32 v4, v62, v74
	v_add_f32_e32 v4, v63, v4
	v_add_f32_e32 v50, v64, v4
	ds_read_b64_tr_b16 v[4:5], v194 offset:30720
	ds_read_b64_tr_b16 v[6:7], v194 offset:31744
	v_add_f32_e32 v50, v17, v50
	s_waitcnt lgkmcnt(2)
	v_mfma_f32_32x32x16_bf16 v[18:33], v[12:15], v[8:11], v[18:33]
	ds_read_b64_tr_b16 v[14:15], v194 offset:31808
	ds_read_b64_tr_b16 v[12:13], v194 offset:30784
	v_cvt_pk_bf16_f32 v11, v64, v17
	v_cvt_pk_bf16_f32 v10, v62, v63
	v_cvt_pk_bf16_f32 v9, v60, v61
	v_cvt_pk_bf16_f32 v8, v58, v59
	s_waitcnt lgkmcnt(2)
	s_nop 0
	v_mfma_f32_32x32x16_bf16 v[34:49], v[4:7], v[8:11], v[34:49]
	ds_bpermute_b32 v4, v175, v50
	s_waitcnt lgkmcnt(0)
	v_add_f32_e32 v4, v50, v4
	v_fmac_f32_e32 v4, v169, v2
	v_mfma_f32_32x32x16_bf16 v[18:33], v[12:15], v[8:11], v[18:33]
	v_mov_b32_e32 v169, v4
